# v65 + XCD-local barriers: the XCC's last arriver writes dirty L2 lines back before releasing (following streaming GEMM phase evicts clean lines)
# speedup vs baseline: 1.0006x; 1.0006x over previous
; __device__ __forceinline__ unsigned xb_ld(unsigned* p)              { return __hip_atomic_load(p, __ATOMIC_RELAXED, __HIP_MEMORY_SCOPE_AGENT); }
; __device__ __forceinline__ unsigned xb_add(unsigned* p, unsigned v) { return __hip_atomic_fetch_add(p, v, __ATOMIC_RELAXED, __HIP_MEMORY_SCOPE_AGENT); }
; #define XB_SPIN(cond, bar) do { unsigned _sp = 0; while (cond) { __builtin_amdgcn_s_sleep(1); \
;     if ((++_sp & 255u) == 0u) { if (xb_ld(&(bar)[XB_TMO])) break; if (_sp > XB_SPIN_CAP) { atomicAdd(&(bar)[XB_TMO], 1u); break; } } } } while (0)
; __device__ __forceinline__ void xcd_barrier(const XcdBarrier& b, bool local = false) {
;     ...
;         const unsigned old = xb_add(&bar[XB_XSUB(b.x)], 1u);
;         const unsigned gen = old / nloc;
;         if (old + 1u == (gen + 1u) * nloc) {
;             if (!local) {
;             __builtin_amdgcn_fence(__ATOMIC_RELEASE, "agent");
;             asm volatile("s_waitcnt vmcnt(0)" ::: "memory");
;             const unsigned og = xb_add(&bar[XB_TOP], 1u);
;             const unsigned tg = og / nx;
;             if (og + 1u == (tg + 1u) * nx) xb_add(&bar[XB_TOPGEN], 1u);
;             else XB_SPIN(xb_ld(&bar[XB_TOPGEN]) == tg, bar);
;             }
;             __builtin_amdgcn_fence(__ATOMIC_ACQUIRE, "agent");
;             xb_add(&bar[XB_XGEN(b.x)], 1u);
;             asm volatile("s_waitcnt vmcnt(0)" ::: "memory");
.LBB0_459:
	s_mov_b64 s[4:5], exec
	v_mbcnt_lo_u32_b32 v1, s4, 0
	v_mbcnt_hi_u32_b32 v1, s5, v1
	v_cmp_eq_u32_e32 vcc, 0, v1
	s_waitcnt vmcnt(0) lgkmcnt(0)
	buffer_wbl2 sc1
	s_waitcnt vmcnt(0)
	buffer_inv sc1
	s_and_saveexec_b64 s[6:7], vcc
	s_cbranch_execz .LBB0_461
	s_bcnt1_i32_b64 s4, s[4:5]
	v_mov_b32_e32 v1, s4
	v_readlane_b32 s4, v253, 61
	v_readlane_b32 s5, v253, 62
	s_nop 4
	global_atomic_add v0, v1, s[4:5]
